# pipelined conv loop with exact vmcnt selected by the previous tile's store count (2/4/0) so waits on prefetched loads no longer drain younger output stores; on top of v42
# speedup vs baseline: 1.0091x; 1.0091x over previous
; __device__ __forceinline__ void conv_phase(CParams& p, int layer, float* smf) {
;     ...
;     const int nCt = 3072 / 64, nRt = MT / 64;
;     for (int t = blockIdx.x; t < nCt * nRt; t += gridDim.x) {
;         const int rt = t / nCt, ct = t - rt * nCt;
;         const int r0 = rt * 64, c0 = ct * 64;
;         const bool first = r0 < ML ? ((r0 & (SEQ - 1)) == 0) : (((r0 - ML) & (CTX - 1)) == 0);
;         const bool last = r0 < ML ? (((r0 + 64) & (SEQ - 1)) == 0) : ((((r0 + 64) - ML) & (CTX - 1)) == 0);
;         lds_sync();
;         for (int e = tid; e < 66 * 8; e += 256) {
;             const int rr = e >> 3, c8 = (e & 7) * 8;
;             const int row = r0 - 1 + rr;
;             u32x4 v = (u32x4){0u, 0u, 0u, 0u};
;             if (!((rr == 0 && first) || (rr == 65 && last))) v = *(const u32x4*)(xbc + (size_t)row * 3072 + c0 + c8);
;             float* d = sin_ + rr * 65 + c8;
;             d[0] = __uint_as_float(v.x << 16); d[1] = __uint_as_float(v.x & 0xffff0000u);
;             d[2] = __uint_as_float(v.y << 16); d[3] = __uint_as_float(v.y & 0xffff0000u);
;             d[4] = __uint_as_float(v.z << 16); d[5] = __uint_as_float(v.z & 0xffff0000u);
;             d[6] = __uint_as_float(v.w << 16); d[7] = __uint_as_float(v.w & 0xffff0000u);
;         }
;         lds_sync();
;         {
;             const int c = tid & 63;
;             const float w0 = cw[c0 + c], w1 = cw[3072 + c0 + c], w2 = cw[2 * 3072 + c0 + c], bb = cb[c0 + c];
.LBB0_402:
	s_mov_b32 s2, s1
	v_readlane_b32 s8, v248, 24
	s_mov_b32 s1, s2
	s_cmp_lg_u32 s2, 8
	v_readlane_b32 s9, v248, 25
	s_cbranch_scc1 .LBB0_422
	v_readlane_b32 s4, v250, 18
	v_readlane_b32 s5, v250, 19
	s_waitcnt vmcnt(29)
	v_mov_b32_e32 v9, v167
	s_andn2_b64 vcc, exec, s[4:5]
	s_cbranch_vccnz .LBB0_422
	s_load_dwordx2 s[4:5], s[8:9], 0xd0
	s_load_dwordx4 s[12:15], s[8:9], 0x90
	s_lshr_b32 s6, s75, 1
	s_waitcnt vmcnt(27)
	v_lshlrev_b32_e32 v0, 4, v9
	s_mul_i32 s8, s6, 0x9000
	s_waitcnt lgkmcnt(0)
	s_add_u32 s46, s4, 0x2700000
	s_addc_u32 s47, s5, 0
	s_mul_i32 s16, s6, 0x3000
	s_add_u32 s6, s4, 0xed00000
	v_and_b32_e32 v8, 48, v0
	s_addc_u32 s7, s5, 0
	v_ashrrev_i32_e32 v19, 2, v9
	v_mul_u32_u24_e32 v0, 0x104, v8
	v_and_b32_e32 v1, -4, v9
	s_add_u32 s8, s12, s8
	s_waitcnt vmcnt(20)
	v_add3_u32 v20, 0, v0, v1
	v_and_b32_e32 v0, 15, v19
	v_lshlrev_b32_e32 v1, 5, v9
	s_addc_u32 s9, s13, 0
	v_and_or_b32 v0, v1, 32, v0
	s_add_u32 s12, s14, s16
	v_lshlrev_b32_e32 v164, 4, v0
	s_addc_u32 s13, s15, 0
	v_and_b32_e32 v16, 63, v9
	v_lshl_add_u64 v[0:1], s[4:5], 0, v[164:165]
	s_mov_b64 s[14:15], 0x13f80000
	v_ashrrev_i32_e32 v2, 6, v9
	v_lshlrev_b32_e32 v3, 2, v16
	v_lshl_add_u64 v[10:11], v[0:1], 0, s[14:15]
	s_mov_b64 s[14:15], 0x15000000
	v_add_u32_e32 v4, 0, v3
	s_waitcnt vmcnt(19)
	v_lshl_add_u64 v[12:13], v[0:1], 0, s[14:15]
	v_mul_lo_u32 v0, v2, s94
	s_movk_i32 s2, 0x210
	v_lshlrev_b32_e32 v5, 8, v16
	v_mul_lo_u32 v6, v19, s94
	v_lshlrev_b32_e32 v7, 2, v8
	v_add_u32_e32 v24, v4, v0
	v_add3_u32 v25, 0, v0, v3
	v_lshlrev_b32_e32 v0, 2, v2
	v_cmp_gt_i32_e64 s[42:43], s2, v9
	v_or_b32_e32 v17, 0xc00, v16
	v_or_b32_e32 v18, 0x1800, v16
	v_or_b32_e32 v21, 0xfffff600, v8
	v_add3_u32 v22, 0, v6, v7
	v_add_u32_e32 v23, 0xfffff800, v19
	v_add3_u32 v26, v4, v5, v0
	v_add_u32_e32 v27, 0x410, v25
	v_add_u32_e32 v28, 0x820, v25
	v_add_u32_e32 v29, 0xc30, v25
	v_add_u32_e32 v30, 0x1040, v25
	v_add_u32_e32 v31, 0x1450, v25
	s_waitcnt vmcnt(15)
	v_add_u32_e32 v32, 0x1860, v25
	v_add_u32_e32 v33, 0x1c70, v25
	v_add_u32_e32 v34, 0x2080, v25
	v_add_u32_e32 v35, 0x2490, v25
	s_waitcnt vmcnt(11)
	v_add_u32_e32 v36, 0x28a0, v25
	v_add_u32_e32 v37, 0x2cb0, v25
	v_add_u32_e32 v38, 0x30c0, v25
	v_add_u32_e32 v39, 0x34d0, v25
	s_waitcnt vmcnt(4)
	v_add_u32_e32 v40, 0x38e0, v25
	v_add_u32_e32 v41, 0x3cf0, v25
	v_lshlrev_b32_e32 v42, 3, v9
	s_mov_b32 s48, s38
	s_mov_b32 s100, s48
	s_mul_hi_i32 s101, s100, 0x2aaaaaab
	s_lshr_b32 s20, s101, 31
	s_ashr_i32 s101, s101, 3
	s_add_i32 s101, s101, s20
	s_mul_i32 s21, s101, 0xffffffd0
	s_add_i32 s21, s21, s100
	s_lshl_b32 s49, s101, 6
	s_lshl_b32 s24, s21, 6
	s_cmpk_lt_i32 s100, 0x3000
	s_cselect_b32 s20, 0x7f, 3
	s_movk_i32 s21, 0x1fc0
	s_cselect_b32 s22, s21, 0xc0
	s_and_b32 s20, s20, s101
	s_cmp_eq_u32 s20, 0
	s_cselect_b64 s[44:45], -1, 0
	s_add_i32 s20, s49, 64
	s_and_b32 s20, s20, s22
	s_cmp_eq_u32 s20, 0
	s_cselect_b64 s[22:23], -1, 0
	s_mov_b32 s101, s24
	s_ashr_i32 s25, s24, 31
	s_lshl_b64 s[24:25], s[24:25], 1
	s_add_u32 s24, s46, s24
	s_addc_u32 s25, s47, s25
	s_add_i32 s49, s49, -1
	s_mov_b64 s[26:27], exec
	v_and_b32_e32 v87, 56, v42
	v_ashrrev_i32_e32 v86, 3, v9
	v_lshlrev_b32_e32 v88, 1, v87
	v_mov_b32_e32 v89, 0
	v_add_u32_e32 v90, s49, v86
	v_mov_b64_e32 v[82:83], s[24:25]
	s_movk_i32 s2, 0x1800
	v_mad_i64_i32 v[82:83], s[50:51], v90, s2, v[82:83]
	v_lshl_add_u64 v[82:83], v[82:83], 0, v[88:89]
	v_mov_b32_e32 v48, 0
	v_mov_b32_e32 v49, 0
	v_mov_b32_e32 v50, 0
	v_mov_b32_e32 v51, 0
	v_mov_b32_e32 v56, 0
	v_mov_b32_e32 v57, 0
	v_mov_b32_e32 v58, 0
	v_mov_b32_e32 v59, 0
	s_mov_b64 s[50:51], 0x60000
	v_lshl_add_u64 v[84:85], v[82:83], 0, s[50:51]
	v_cmp_gt_u32_e64 s[50:51], 8, v9
	v_cmp_gt_u32_e32 vcc, 16, v9
	s_nop 1
	s_andn2_b64 s[20:21], vcc, s[22:23]
	s_or_b64 s[50:51], s[50:51], s[20:21]
	s_and_b64 exec, s[26:27], s[50:51]
	global_load_dwordx4 v[56:59], v[84:85], off
	s_mov_b64 exec, s[26:27]
	v_cmp_gt_u32_e32 vcc, 8, v9
	s_nop 1
	s_and_b64 s[50:51], s[44:45], vcc
	s_andn2_b64 exec, s[26:27], s[50:51]
	global_load_dwordx4 v[48:51], v[82:83], off
	s_mov_b64 exec, s[26:27]
	s_mov_b64 s[50:51], 0x30000
	v_lshl_add_u64 v[84:85], v[82:83], 0, s[50:51]
	global_load_dwordx4 v[52:55], v[84:85], off
	v_or_b32_e32 v60, s101, v16
	v_ashrrev_i32_e32 v61, 31, v60
	v_add_u32_e32 v62, s101, v17
	v_lshlrev_b64 v[64:65], 2, v[60:61]
	v_ashrrev_i32_e32 v63, 31, v62
	v_lshl_add_u64 v[60:61], s[8:9], 0, v[64:65]
	v_lshl_add_u64 v[62:63], v[62:63], 2, s[8:9]
	global_load_dword v66, v[60:61], off
	v_lshl_add_u64 v[64:65], s[12:13], 0, v[64:65]
	global_load_dword v67, v[62:63], off
	v_add_u32_e32 v62, s101, v18
	v_ashrrev_i32_e32 v63, 31, v62
	v_lshl_add_u64 v[62:63], v[62:63], 2, s[8:9]
	global_load_dword v68, v[62:63], off
	global_load_dword v69, v[64:65], off
	s_mov_b32 s100, 0
	s_branch .LBB0_406

; __device__ __forceinline__ void conv_phase(CParams& p, int layer, float* smf) {
;     ...
;         lds_sync();
;         for (int e = tid; e < 66 * 8; e += 256) {
;             const int rr = e >> 3, c8 = (e & 7) * 8;
;             const int row = r0 - 1 + rr;
;             u32x4 v = (u32x4){0u, 0u, 0u, 0u};
;             if (!((rr == 0 && first) || (rr == 65 && last))) v = *(const u32x4*)(xbc + (size_t)row * 3072 + c0 + c8);
;             float* d = sin_ + rr * 65 + c8;
;             d[0] = __uint_as_float(v.x << 16); d[1] = __uint_as_float(v.x & 0xffff0000u);
;             d[2] = __uint_as_float(v.y << 16); d[3] = __uint_as_float(v.y & 0xffff0000u);
;             d[4] = __uint_as_float(v.z << 16); d[5] = __uint_as_float(v.z & 0xffff0000u);
;             d[6] = __uint_as_float(v.w << 16); d[7] = __uint_as_float(v.w & 0xffff0000u);
;         }
;         lds_sync();
;         {
;             const int c = tid & 63;
;             const float w0 = cw[c0 + c], w1 = cw[3072 + c0 + c], w2 = cw[2 * 3072 + c0 + c], bb = cb[c0 + c];
.LBB0_406:
	s_mul_hi_i32 s14, s48, 0x2aaaaaab
	s_lshr_b32 s15, s14, 31
	s_ashr_i32 s17, s14, 3
	s_add_i32 s17, s17, s15
	s_mul_i32 s15, s17, 0xffffffd0
	s_add_i32 s15, s15, s48
	s_lshl_b32 s14, s17, 6
	s_lshl_b32 s16, s15, 6
	s_waitcnt vmcnt(63) expcnt(7) lgkmcnt(15)
	s_barrier
	s_and_saveexec_b64 s[18:19], s[42:43]
	s_cbranch_execz .LBB0_411
	s_mov_b64 s[26:27], exec
	v_and_b32_e32 v7, 56, v42
	v_ashrrev_i32_e32 v6, 3, v9
	v_mul_lo_u32 v70, v6, s94
	v_lshlrev_b32_e32 v71, 2, v7
	v_add3_u32 v70, 0, v70, v71
	v_add_u32_e32 v71, 0x2080, v70
	v_add_u32_e32 v72, 0x4100, v70
	s_cmp_eq_u32 s100, 4
	s_cbranch_scc1 .Lcv_a4
	s_cmp_eq_u32 s100, 2
	s_cbranch_scc1 .Lcv_a2
	s_waitcnt vmcnt(5)
	s_branch .Lcv_ad
.Lcv_a2:
	s_waitcnt vmcnt(7)
	s_branch .Lcv_ad
.Lcv_a4:
	s_waitcnt vmcnt(9)
.Lcv_ad:
	v_lshlrev_b32_e32 v73, 16, v48
	v_and_b32_e32 v74, 0xffff0000, v48
	ds_write2_b32 v70, v73, v74 offset1:1
	v_lshlrev_b32_e32 v75, 16, v49
	v_and_b32_e32 v76, 0xffff0000, v49
	ds_write2_b32 v70, v75, v76 offset0:2 offset1:3
	v_lshlrev_b32_e32 v73, 16, v50
	v_and_b32_e32 v74, 0xffff0000, v50
	ds_write2_b32 v70, v73, v74 offset0:4 offset1:5
	v_lshlrev_b32_e32 v75, 16, v51
	v_and_b32_e32 v76, 0xffff0000, v51
	ds_write2_b32 v70, v75, v76 offset0:6 offset1:7
	s_cmp_eq_u32 s100, 4
	s_cbranch_scc1 .Lcv_b4
	s_cmp_eq_u32 s100, 2
	s_cbranch_scc1 .Lcv_b2
	s_waitcnt vmcnt(4)
	s_branch .Lcv_bd
.Lcv_b2:
	s_waitcnt vmcnt(6)
	s_branch .Lcv_bd
.Lcv_b4:
	s_waitcnt vmcnt(8)
.Lcv_bd:
	v_lshlrev_b32_e32 v73, 16, v52
	v_and_b32_e32 v74, 0xffff0000, v52
	ds_write2_b32 v71, v73, v74 offset1:1
	v_lshlrev_b32_e32 v75, 16, v53
	v_and_b32_e32 v76, 0xffff0000, v53
	ds_write2_b32 v71, v75, v76 offset0:2 offset1:3
	v_lshlrev_b32_e32 v73, 16, v54
	v_and_b32_e32 v74, 0xffff0000, v54
	ds_write2_b32 v71, v73, v74 offset0:4 offset1:5
	v_lshlrev_b32_e32 v75, 16, v55
	v_and_b32_e32 v76, 0xffff0000, v55
	ds_write2_b32 v71, v75, v76 offset0:6 offset1:7
	v_cmp_gt_u32_e32 vcc, 16, v9
	s_nop 1
	s_and_b64 exec, s[26:27], vcc
	v_lshlrev_b32_e32 v73, 16, v56
	v_and_b32_e32 v74, 0xffff0000, v56
	ds_write2_b32 v72, v73, v74 offset1:1
	v_lshlrev_b32_e32 v75, 16, v57
	v_and_b32_e32 v76, 0xffff0000, v57
	ds_write2_b32 v72, v75, v76 offset0:2 offset1:3
	v_lshlrev_b32_e32 v73, 16, v58
	v_and_b32_e32 v74, 0xffff0000, v58
	ds_write2_b32 v72, v73, v74 offset0:4 offset1:5
	v_lshlrev_b32_e32 v75, 16, v59
	v_and_b32_e32 v76, 0xffff0000, v59
	ds_write2_b32 v72, v75, v76 offset0:6 offset1:7
	s_mov_b64 exec, s[26:27]
.LBB0_411:
	s_or_b64 exec, exec, s[18:19]
	v_or_b32_e32 v0, s16, v16
	v_ashrrev_i32_e32 v1, 31, v0
	v_add_u32_e32 v2, s16, v17
	v_lshlrev_b64 v[4:5], 2, v[0:1]
	v_ashrrev_i32_e32 v3, 31, v2
	v_lshl_add_u64 v[0:1], s[8:9], 0, v[4:5]
	v_lshl_add_u64 v[2:3], v[2:3], 2, s[8:9]
	s_waitcnt lgkmcnt(0)
	s_barrier
	s_cmp_eq_u32 s100, 4
	s_cbranch_scc1 .Lcv_c4
	s_cmp_eq_u32 s100, 2
	s_cbranch_scc1 .Lcv_c2
	s_waitcnt vmcnt(0)
	s_branch .Lcv_cd
.Lcv_c2:
	s_waitcnt vmcnt(2)
	s_branch .Lcv_cd
.Lcv_c4:
	s_waitcnt vmcnt(4)
.Lcv_cd:
	v_mov_b32_e32 v0, v66
	v_mov_b32_e32 v1, v67
	v_mov_b32_e32 v2, v68
	v_mov_b32_e32 v3, v69
	s_add_i32 s100, s48, s74
	s_cmpk_lt_i32 s100, 0x3180
	s_cbranch_scc0 .Lconv_nopf
	s_mul_hi_i32 s101, s100, 0x2aaaaaab
	s_lshr_b32 s20, s101, 31
	s_ashr_i32 s101, s101, 3
	s_add_i32 s101, s101, s20
	s_mul_i32 s21, s101, 0xffffffd0
	s_add_i32 s21, s21, s100
	s_lshl_b32 s49, s101, 6
	s_lshl_b32 s24, s21, 6
	s_cmpk_lt_i32 s100, 0x3000
	s_cselect_b32 s20, 0x7f, 3
	s_movk_i32 s21, 0x1fc0
	s_cselect_b32 s22, s21, 0xc0
	s_and_b32 s20, s20, s101
	s_cmp_eq_u32 s20, 0
	s_cselect_b64 s[44:45], -1, 0
	s_add_i32 s20, s49, 64
	s_and_b32 s20, s20, s22
	s_cmp_eq_u32 s20, 0
	s_cselect_b64 s[22:23], -1, 0
	s_mov_b32 s101, s24
	s_ashr_i32 s25, s24, 31
	s_lshl_b64 s[24:25], s[24:25], 1
	s_add_u32 s24, s46, s24
	s_addc_u32 s25, s47, s25
	s_add_i32 s49, s49, -1
	s_mov_b64 s[26:27], exec
	v_and_b32_e32 v87, 56, v42
	v_ashrrev_i32_e32 v86, 3, v9
	v_lshlrev_b32_e32 v88, 1, v87
	v_mov_b32_e32 v89, 0
	v_add_u32_e32 v90, s49, v86
	v_mov_b64_e32 v[82:83], s[24:25]
	s_movk_i32 s2, 0x1800
	v_mad_i64_i32 v[82:83], s[50:51], v90, s2, v[82:83]
	v_lshl_add_u64 v[82:83], v[82:83], 0, v[88:89]
	v_mov_b32_e32 v48, 0
	v_mov_b32_e32 v49, 0
	v_mov_b32_e32 v50, 0
	v_mov_b32_e32 v51, 0
	v_mov_b32_e32 v56, 0
	v_mov_b32_e32 v57, 0
	v_mov_b32_e32 v58, 0
	v_mov_b32_e32 v59, 0
	s_mov_b64 s[50:51], 0x60000
	v_lshl_add_u64 v[84:85], v[82:83], 0, s[50:51]
	v_cmp_gt_u32_e64 s[50:51], 8, v9
	v_cmp_gt_u32_e32 vcc, 16, v9
	s_nop 1
	s_andn2_b64 s[20:21], vcc, s[22:23]
	s_or_b64 s[50:51], s[50:51], s[20:21]
	s_and_b64 exec, s[26:27], s[50:51]
	global_load_dwordx4 v[56:59], v[84:85], off
	s_mov_b64 exec, s[26:27]
	v_cmp_gt_u32_e32 vcc, 8, v9
	s_nop 1
	s_and_b64 s[50:51], s[44:45], vcc
	s_andn2_b64 exec, s[26:27], s[50:51]
	global_load_dwordx4 v[48:51], v[82:83], off
	s_mov_b64 exec, s[26:27]
	s_mov_b64 s[50:51], 0x30000
	v_lshl_add_u64 v[84:85], v[82:83], 0, s[50:51]
	global_load_dwordx4 v[52:55], v[84:85], off
	v_or_b32_e32 v60, s101, v16
	v_ashrrev_i32_e32 v61, 31, v60
	v_add_u32_e32 v62, s101, v17
	v_lshlrev_b64 v[64:65], 2, v[60:61]
	v_ashrrev_i32_e32 v63, 31, v62
	v_lshl_add_u64 v[60:61], s[8:9], 0, v[64:65]
	v_lshl_add_u64 v[62:63], v[62:63], 2, s[8:9]
	global_load_dword v66, v[60:61], off
	v_lshl_add_u64 v[64:65], s[12:13], 0, v[64:65]
	global_load_dword v67, v[62:63], off
	v_add_u32_e32 v62, s101, v18
	v_ashrrev_i32_e32 v63, 31, v62
	v_lshl_add_u64 v[62:63], v[62:63], 2, s[8:9]
	global_load_dword v68, v[62:63], off
	global_load_dword v69, v[64:65], off
	s_add_i32 s100, s15, -32
	s_cmp_lt_u32 s100, 8
	s_cselect_b32 s100, 4, 2
